# GEMM unit boundary: next unit (pn,pm) derived incrementally from the current unit (pn+=4, wrap -> pm+=8) instead of the 60-instruction from-scratch decode with a v_rcp division; plus zeroing trims
# speedup vs baseline: 1.0069x; 1.0006x over previous
.LBB0_35:
	s_add_i32 s51, s51, 1
	s_mul_i32 s0, s51, s50
	s_mul_hi_u32 s1, s51, s34
	s_add_i32 s1, s1, s0
	s_mul_i32 s0, s51, s34
	s_add_u32 s20, s0, s62
	s_addc_u32 s21, s1, s63
	v_cmp_gt_i64_e32 vcc, s[20:21], v[132:133]
	v_cmp_lt_i64_e64 s[0:1], s[20:21], v[130:131]
	s_cbranch_vccnz .LBB0_41
	s_add_i32 s52, s54, 4
	s_mov_b32 s53, s55
	s_cmp_lt_i32 s52, 4
	s_cbranch_scc1 .Ldec_0
	s_sub_i32 s52, s52, 4
	s_add_i32 s53, s55, 8
.Ldec_0:
.LBB0_41:
	s_nop 0
	v_cndmask_b32_e64 v0, 0, 1, s[0:1]
	v_cmp_ne_u32_e64 s[40:41], 1, v0
	s_andn2_b64 vcc, exec, s[0:1]
	s_mov_b64 s[20:21], s[28:29]
	s_cbranch_vccnz .LBB0_43
	s_ashr_i32 s0, s53, 31
	s_mul_hi_u32 s1, s6, s53
	s_mul_i32 s0, s6, s0
	s_add_i32 s0, s1, s0
	s_mul_i32 s1, s7, s53
	s_add_i32 s0, s0, s1
	s_mul_i32 s1, s6, s53
	s_add_u32 s20, s22, s1
	s_addc_u32 s21, s23, s0

.LBB0_95:
	s_add_i32 s49, s49, 1
	s_mul_i32 s0, s49, s48
	s_mul_hi_u32 s1, s49, s28
	s_add_i32 s1, s1, s0
	s_mul_i32 s0, s49, s28
	s_add_u32 s20, s0, s62
	s_addc_u32 s21, s1, s63
	v_mov_b64_e32 v[0:1], 0xb00
	v_cmp_lt_i64_e64 s[0:1], s[20:21], v[0:1]
	v_mov_b64_e32 v[0:1], 0xaff
	v_cmp_gt_i64_e32 vcc, s[20:21], v[0:1]
	s_cbranch_vccnz .LBB0_97
	s_add_i32 s50, s52, 4
	s_mov_b32 s51, s53
	s_cmp_lt_i32 s50, 22
	s_cbranch_scc1 .Ldec_1
	s_sub_i32 s50, s50, 22
	s_add_i32 s51, s53, 8
.Ldec_1:
.LBB0_97:
	v_cndmask_b32_e64 v0, 0, 1, s[0:1]
	v_cmp_ne_u32_e64 s[40:41], 1, v0
	s_andn2_b64 vcc, exec, s[0:1]
	s_mov_b64 s[0:1], s[24:25]
	s_cbranch_vccnz .LBB0_99
	s_ashr_i32 s0, s51, 31
	s_mul_hi_u32 s1, s6, s51
	s_mul_i32 s0, s6, s0
	s_add_i32 s0, s1, s0
	s_mul_i32 s1, s7, s51
	s_add_i32 s1, s0, s1
	s_mul_i32 s0, s6, s51
	s_add_u32 s0, s8, s0
	s_addc_u32 s1, s9, s1

.LBB0_127:
	s_add_i32 s49, s49, 1
	s_mul_i32 s0, s49, s48
	s_mul_hi_u32 s1, s49, s34
	s_add_i32 s1, s1, s0
	s_mul_i32 s0, s49, s34
	s_add_u32 s20, s0, s62
	s_addc_u32 s21, s1, s63
	v_cmp_gt_i64_e32 vcc, s[20:21], v[132:133]
	v_cmp_lt_i64_e64 s[0:1], s[20:21], v[130:131]
	s_cbranch_vccnz .LBB0_133
	s_add_i32 s50, s52, 4
	s_mov_b32 s51, s53
	s_cmp_lt_i32 s50, 4
	s_cbranch_scc1 .Ldec_2
	s_sub_i32 s50, s50, 4
	s_add_i32 s51, s53, 8
.Ldec_2:
.LBB0_133:
	s_nop 0
	v_cndmask_b32_e64 v0, 0, 1, s[0:1]
	v_cmp_ne_u32_e64 s[40:41], 1, v0
	s_andn2_b64 vcc, exec, s[0:1]
	s_mov_b64 s[20:21], s[28:29]
	s_cbranch_vccnz .LBB0_135
	s_ashr_i32 s0, s51, 31
	s_mul_hi_u32 s1, s6, s51
	s_mul_i32 s0, s6, s0
	s_add_i32 s0, s1, s0
	s_mul_i32 s1, s7, s51
	s_add_i32 s0, s0, s1
	s_mul_i32 s1, s6, s51
	s_add_u32 s20, s8, s1
	s_addc_u32 s21, s9, s0

.LBB0_327:
	s_add_i32 s49, s49, 1
	s_mul_i32 s0, s49, s48
	s_mul_hi_u32 s1, s49, s43
	s_add_i32 s1, s1, s0
	s_mul_i32 s0, s49, s43
	s_add_u32 s20, s0, s62
	s_addc_u32 s21, s1, s63
	v_mov_b64_e32 v[0:1], 0x800
	v_cmp_gt_i64_e32 vcc, s[20:21], v[138:139]
	v_cmp_lt_i64_e64 s[0:1], s[20:21], v[0:1]
	s_cbranch_vccnz .LBB0_333
	s_add_i32 s50, s52, 4
	s_mov_b32 s51, s53
	s_cmp_lt_i32 s50, 16
	s_cbranch_scc1 .Ldec_3
	s_sub_i32 s50, s50, 16
	s_add_i32 s51, s53, 8
